# diff attention row-sum MFMA 32x32x16 -> 16x16x32 (half the matrix-pipe time, same bf16 x 1.0 f32-accumulate numerics)
# speedup vs baseline: 1.0495x; 1.0168x over previous
.LBB0_532:
	v_mov_b32_e32 v214, 0
	v_mov_b32_e32 v215, 0
	v_mov_b32_e32 v216, 0
	v_mov_b32_e32 v217, 0
	s_ashr_i32 s10, s2, 2
	s_and_b32 s7, s2, 3
	s_lshl_b32 s53, s10, 3
	s_lshl_b32 s79, s7, 1
	s_or_b32 s0, s53, s79
	s_ashr_i32 s1, s0, 31
	s_lshl_b64 s[0:1], s[0:1], 19
	s_add_u32 s26, s71, s0
	s_addc_u32 s27, s72, s1
	s_add_u32 s0, s73, s0
	s_addc_u32 s1, s74, s1
	s_add_u32 s13, s0, 0x80000
	s_addc_u32 s30, s1, 0
	s_ashr_i32 s3, s2, 31
	s_lshl_b64 s[34:35], s[2:3], 20
	s_add_u32 s29, s75, s34
	s_addc_u32 s33, s76, s35
	s_lshl_b32 s2, s42, 3
	s_add_i32 s2, s6, s2
	v_and_b32_e32 v2, 31, v1
	s_ashr_i32 s3, s2, 31
	v_bfe_u32 v0, v1, 5, 1
	v_lshlrev_b32_e32 v172, 4, v2
	s_lshl_b64 s[2:3], s[2:3], 11
	v_lshl_or_b32 v4, v0, 9, s2
	v_mov_b32_e32 v5, s3
	v_lshl_add_u64 v[6:7], s[26:27], 0, v[172:173]
	v_lshl_add_u64 v[4:5], v[6:7], 0, v[4:5]
	global_load_dwordx4 v[50:53], v[4:5], off nt
	global_load_dwordx4 v[54:57], v[4:5], off offset:1024 nt
	v_lshl_add_u64 v[6:7], v[4:5], 0, s[88:89]
	v_add_co_u32_e32 v4, vcc, 0x80000, v4
	v_and_b32_e32 v1, 63, v1
	s_nop 0
	v_addc_co_u32_e32 v5, vcc, 0, v5, vcc
	global_load_dwordx4 v[178:181], v[4:5], off nt
	global_load_dwordx4 v[174:177], v[6:7], off offset:1024 nt
	v_cndmask_b32_e64 v3, 0, 1, s[4:5]
	v_lshlrev_b32_e32 v1, 4, v1
	v_cmp_ne_u32_e64 s[38:39], 1, v3
	s_andn2_b64 vcc, exec, s[4:5]
	s_mov_b64 s[2:3], -1
	s_cbranch_vccz .LBB0_549
	s_andn2_b64 vcc, exec, s[2:3]
	s_cbranch_vccz .LBB0_550

.LBB0_536:
	v_lshl_or_b32 v186, v0, 10, v172
	v_add_u32_e32 v74, 0, v186
	s_waitcnt vmcnt(3)
	s_waitcnt vmcnt(2)
	s_waitcnt vmcnt(1)
	s_waitcnt vmcnt(0)
	ds_read_b128 v[4:7], v74
	ds_read_b128 v[8:11], v74 offset:512
	s_waitcnt lgkmcnt(0)
	v_mfma_f32_32x32x16_bf16 v[76:91], v[8:11], v[50:53], 0
	ds_read_b128 v[8:11], v74 offset:2048
	ds_read_b128 v[12:15], v74 offset:2560
	s_lshl_b32 s2, s42, 8
	s_lshl_b32 s31, s6, 5
	s_add_i32 s4, s31, s2
	s_lshl_b32 s51, s7, 6
	s_lshl_b32 s7, s42, 2
	s_lshl_b32 s3, s10, 13
	s_waitcnt lgkmcnt(0)
	v_mfma_f32_32x32x16_bf16 v[76:91], v[12:15], v[54:57], v[76:91]
	s_ashr_i32 s9, s4, 6
	s_add_i32 s27, s7, 4
	s_add_i32 s52, s3, s2
	v_mfma_f32_32x32x16_bf16 v[92:107], v[4:7], v[50:53], 0
	s_or_b32 s28, s7, 2
	v_mov_b32_e32 v0, v173
	s_cmp_lt_i32 s9, 0
	s_mov_b64 s[2:3], -1
	v_mfma_f32_32x32x16_bf16 v[92:107], v[8:11], v[54:57], v[92:107]
	s_cbranch_scc1 .LBB0_575
	s_cmp_lt_u32 s4, 64
	s_cbranch_scc1 .LBB0_551
	s_lshl_b32 s2, s6, 10
	s_and_b32 s5, s2, 0xc00
	v_mov_b32_e32 v3, 0x3f803f80
	v_cmp_eq_u32_e32 vcc, 0, v2
	s_nop 1
	v_cndmask_b32_e32 v58, 0, v3, vcc
	v_cmp_eq_u32_e32 vcc, 17, v2
	s_nop 1
	v_cndmask_b32_e32 v58, v58, v3, vcc
	v_cmp_eq_u32_e32 vcc, 2, v2
	s_nop 1
	v_cndmask_b32_e32 v62, 0, v3, vcc
	v_cmp_eq_u32_e32 vcc, 19, v2
	s_nop 1
	v_cndmask_b32_e32 v62, v62, v3, vcc
	s_add_i32 s2, s53, s79
	s_ashr_i32 s3, s2, 31
	s_or_b32 s40, s5, 0x1000
	s_or_b32 s41, s5, 0x2000
	s_or_b32 s42, s5, 0x3000
	s_max_u32 s26, s9, 1
	s_lshl_b64 s[2:3], s[2:3], 19
	s_add_u32 s44, s18, s2
	s_addc_u32 s45, s19, s3
	s_add_u32 s46, s18, s34
	v_mov_b32_e32 v59, v58
	v_mov_b32_e32 v60, v58
	v_mov_b32_e32 v61, v58
	v_mov_b32_e32 v63, v62
	v_mov_b32_e32 v64, v62
	v_mov_b32_e32 v65, v62
	s_mov_b32 s43, 1
	s_addc_u32 s47, s19, s35
	v_mov_b32_e32 v108, v0
	v_mov_b32_e32 v109, v0
	v_mov_b32_e32 v110, v0
	v_mov_b32_e32 v111, v0
	v_mov_b32_e32 v112, v0
	v_mov_b32_e32 v113, v0
	v_mov_b32_e32 v114, v0
	v_mov_b32_e32 v115, v0
	v_mov_b32_e32 v116, v0
	v_mov_b32_e32 v117, v0
	v_mov_b32_e32 v118, v0
	v_mov_b32_e32 v119, v0
	v_mov_b32_e32 v120, v0
	v_mov_b32_e32 v121, v0
	v_mov_b32_e32 v122, v0
	v_mov_b32_e32 v123, v0
	v_mov_b32_e32 v124, v0
	v_mov_b32_e32 v125, v0
	v_mov_b32_e32 v126, v0
	v_mov_b32_e32 v127, v0
	v_mov_b32_e32 v128, v0
	v_mov_b32_e32 v129, v0
	v_mov_b32_e32 v130, v0
	v_mov_b32_e32 v131, v0
	v_mov_b32_e32 v132, v0
	v_mov_b32_e32 v133, v0
	v_mov_b32_e32 v134, v0
	v_mov_b32_e32 v135, v0
	v_mov_b32_e32 v136, v0
	v_mov_b32_e32 v137, v0
	v_mov_b32_e32 v138, v0
	v_mov_b32_e32 v139, v0
	v_mov_b32_e32 v140, v0
	v_mov_b32_e32 v141, v0
	v_mov_b32_e32 v142, v0
	v_mov_b32_e32 v143, v0
	v_mov_b32_e32 v144, v0
	v_mov_b32_e32 v145, v0
	v_mov_b32_e32 v146, v0
	v_mov_b32_e32 v147, v0
	v_mov_b32_e32 v148, v0
	v_mov_b32_e32 v149, v0
	v_mov_b32_e32 v150, v0
	v_mov_b32_e32 v151, v0
	v_mov_b32_e32 v152, v0
	v_mov_b32_e32 v153, v0
	v_mov_b32_e32 v154, v0
	v_mov_b32_e32 v155, v0
	v_mov_b32_e32 v2, v0
	v_mov_b32_e32 v3, v0
	v_mov_b32_e32 v4, v0
	v_mov_b32_e32 v5, v0
	v_mov_b32_e32 v6, v0
	v_mov_b32_e32 v7, v0
	v_mov_b32_e32 v8, v0
	v_mov_b32_e32 v9, v0
	v_mov_b32_e32 v10, v0
	v_mov_b32_e32 v11, v0
	v_mov_b32_e32 v12, v0
	v_mov_b32_e32 v13, v0
	v_mov_b32_e32 v14, v0
	v_mov_b32_e32 v15, v0
	v_mov_b32_e32 v16, v0
	v_mov_b32_e32 v17, v0
	v_mov_b32_e32 v156, v0
	v_mov_b32_e32 v157, v0
	v_mov_b32_e32 v158, v0
	v_mov_b32_e32 v159, v0
	v_mov_b32_e32 v160, v0
	v_mov_b32_e32 v161, v0
	v_mov_b32_e32 v162, v0
	v_mov_b32_e32 v163, v0
	v_mov_b32_e32 v164, v0
	v_mov_b32_e32 v165, v0
	v_mov_b32_e32 v166, v0
	v_mov_b32_e32 v167, v0
	v_mov_b32_e32 v168, v0
	v_mov_b32_e32 v169, v0
	v_mov_b32_e32 v170, v0
	v_mov_b32_e32 v171, v0
	s_add_i32 s9, s43, -1
	s_cmp_ge_u32 s9, s28
	s_mov_b64 s[2:3], -1
	s_cbranch_scc0 .LBB0_540

.LBB0_547:
	s_and_b32 s2, s9, 3
	s_mulk_i32 s2, 0x5000
	v_add_u32_e32 v75, s2, v74
	ds_read_b128 v[18:21], v75 offset:8704
	ds_read_b128 v[22:25], v75 offset:8192
	ds_read_b128 v[26:29], v75 offset:4096
	v_exp_f32_e32 v92, v92
	v_exp_f32_e32 v93, v93
	v_exp_f32_e32 v94, v94
	v_exp_f32_e32 v95, v95
	v_exp_f32_e32 v96, v96
	v_exp_f32_e32 v97, v97
	v_exp_f32_e32 v98, v98
	v_exp_f32_e32 v99, v99
	v_cvt_pk_bf16_f32 v70, v92, v93
	v_cvt_pk_bf16_f32 v71, v94, v95
	v_cvt_pk_bf16_f32 v72, v96, v97
	v_cvt_pk_bf16_f32 v73, v98, v99
	s_waitcnt lgkmcnt(1)
	s_nop 0
	v_mfma_f32_32x32x16_bf16 v[156:171], v[22:25], v[70:73], v[156:171]
	ds_read_b128 v[30:33], v75 offset:10240
	s_mov_b32 s10, s8
	s_mov_b32 s11, s8
	s_mov_b32 s9, s8
	v_exp_f32_e32 v100, v100
	v_exp_f32_e32 v101, v101
	v_exp_f32_e32 v102, v102
	v_mfma_f32_32x32x16_bf16 v[140:155], v[18:21], v[70:73], v[140:155]
	ds_read_b128 v[18:21], v75 offset:10752
	v_exp_f32_e32 v103, v103
	v_exp_f32_e32 v104, v104
	v_exp_f32_e32 v105, v105
	v_mfma_f32_16x16x32_bf16 v[214:217], v[58:61], v[70:73], v[214:217]
	v_exp_f32_e32 v106, v106
	v_exp_f32_e32 v107, v107
	v_cvt_pk_bf16_f32 v182, v100, v101
	ds_read_b128 v[22:25], v75 offset:4608
	v_cvt_pk_bf16_f32 v183, v102, v103
	v_cvt_pk_bf16_f32 v184, v104, v105
	v_cvt_pk_bf16_f32 v185, v106, v107
	s_waitcnt lgkmcnt(3)
	v_mfma_f32_32x32x16_bf16 v[34:49], v[26:29], v[178:181], 0
	s_waitcnt lgkmcnt(2)
	v_mfma_f32_32x32x16_bf16 v[156:171], v[30:33], v[182:185], v[156:171]
	ds_read_b128 v[92:95], v75 offset:12288
	v_exp_f32_e32 v76, v76
	v_exp_f32_e32 v77, v77
	v_exp_f32_e32 v78, v78
	s_waitcnt lgkmcnt(2)
	v_mfma_f32_32x32x16_bf16 v[140:155], v[18:21], v[182:185], v[140:155]
	ds_read_b128 v[96:99], v75 offset:12800
	v_exp_f32_e32 v79, v79
	v_exp_f32_e32 v80, v80
	v_exp_f32_e32 v81, v81
	v_mfma_f32_16x16x32_bf16 v[214:217], v[58:61], v[182:185], v[214:217]
	v_exp_f32_e32 v82, v82
	v_exp_f32_e32 v83, v83
	v_cvt_pk_bf16_f32 v70, v76, v77
	ds_read_b128 v[100:103], v75 offset:6144
	v_cvt_pk_bf16_f32 v71, v78, v79
	v_cvt_pk_bf16_f32 v72, v80, v81
	v_cvt_pk_bf16_f32 v73, v82, v83
	s_waitcnt lgkmcnt(3)
	v_mfma_f32_32x32x16_bf16 v[18:33], v[22:25], v[178:181], 0
	s_waitcnt lgkmcnt(2)
	v_mfma_f32_32x32x16_bf16 v[156:171], v[92:95], v[70:73], v[156:171]
	ds_read_b128 v[92:95], v75 offset:14336
	v_exp_f32_e32 v84, v84
	v_exp_f32_e32 v85, v85
	v_exp_f32_e32 v86, v86
	s_waitcnt lgkmcnt(2)
	v_mfma_f32_32x32x16_bf16 v[140:155], v[96:99], v[70:73], v[140:155]
	ds_read_b128 v[96:99], v75 offset:14848
	v_exp_f32_e32 v87, v87
	v_exp_f32_e32 v88, v88
	v_exp_f32_e32 v89, v89
	v_mfma_f32_16x16x32_bf16 v[214:217], v[58:61], v[70:73], v[214:217]
	v_exp_f32_e32 v90, v90
	v_exp_f32_e32 v91, v91
	v_cvt_pk_bf16_f32 v182, v84, v85
	ds_read_b128 v[70:73], v75 offset:6656
	v_cvt_pk_bf16_f32 v183, v86, v87
	v_cvt_pk_bf16_f32 v184, v88, v89
	v_cvt_pk_bf16_f32 v185, v90, v91
	s_waitcnt lgkmcnt(3)
	v_mfma_f32_32x32x16_bf16 v[34:49], v[100:103], v[174:177], v[34:49]
	s_waitcnt lgkmcnt(2)
	v_mfma_f32_32x32x16_bf16 v[156:171], v[92:95], v[182:185], v[156:171]
	s_waitcnt lgkmcnt(1)
	v_mfma_f32_32x32x16_bf16 v[140:155], v[96:99], v[182:185], v[140:155]
	v_mfma_f32_16x16x32_bf16 v[214:217], v[58:61], v[182:185], v[214:217]
	s_waitcnt lgkmcnt(0)
	v_mfma_f32_32x32x16_bf16 v[18:33], v[70:73], v[174:177], v[18:33]
	s_and_b32 s2, s43, 3
	s_mulk_i32 s2, 0x5000
	v_add_u32_e32 v172, s2, v74
	ds_read_b128 v[76:79], v75 offset:8192
	ds_read_b128 v[80:83], v75 offset:8704
	ds_read_b128 v[84:87], v172
	v_exp_f32_e32 v34, v34
	v_exp_f32_e32 v35, v35
	v_exp_f32_e32 v36, v36
	v_exp_f32_e32 v37, v37
	v_exp_f32_e32 v38, v38
	v_exp_f32_e32 v39, v39
	v_exp_f32_e32 v40, v40
	v_exp_f32_e32 v41, v41
	v_cvt_pk_bf16_f32 v70, v34, v35
	v_cvt_pk_bf16_f32 v71, v36, v37
	v_cvt_pk_bf16_f32 v72, v38, v39
	v_cvt_pk_bf16_f32 v73, v40, v41
	s_waitcnt lgkmcnt(2)
	s_nop 0
	v_mfma_f32_32x32x16_bf16 v[124:139], v[76:79], v[70:73], v[124:139]
	ds_read_b128 v[76:79], v75 offset:10240
	v_exp_f32_e32 v42, v42
	v_exp_f32_e32 v43, v43
	v_exp_f32_e32 v44, v44
	s_waitcnt lgkmcnt(2)
	v_mfma_f32_32x32x16_bf16 v[108:123], v[80:83], v[70:73], v[108:123]
	ds_read_b128 v[80:83], v75 offset:10752
	v_exp_f32_e32 v45, v45
	v_exp_f32_e32 v46, v46
	v_exp_f32_e32 v47, v47
	v_mfma_f32_16x16x32_bf16 v[214:217], v[62:65], v[70:73], v[214:217]
	v_exp_f32_e32 v48, v48
	v_exp_f32_e32 v49, v49
	v_cvt_pk_bf16_f32 v66, v42, v43
	s_waitcnt lgkmcnt(2)
	v_mfma_f32_32x32x16_bf16 v[92:107], v[84:87], v[50:53], 0
	ds_read_b128 v[88:91], v172 offset:512
	v_cvt_pk_bf16_f32 v67, v44, v45
	v_cvt_pk_bf16_f32 v68, v46, v47
	v_cvt_pk_bf16_f32 v69, v48, v49
	s_waitcnt lgkmcnt(2)
	s_nop 0
	v_mfma_f32_32x32x16_bf16 v[124:139], v[76:79], v[66:69], v[124:139]
	ds_read_b128 v[34:37], v75 offset:12288
	v_exp_f32_e32 v18, v18
	v_exp_f32_e32 v19, v19
	v_exp_f32_e32 v20, v20
	s_waitcnt lgkmcnt(2)
	v_mfma_f32_32x32x16_bf16 v[108:123], v[80:83], v[66:69], v[108:123]
	ds_read_b128 v[38:41], v75 offset:12800
	v_exp_f32_e32 v21, v21
	v_exp_f32_e32 v22, v22
	v_exp_f32_e32 v23, v23
	v_mfma_f32_16x16x32_bf16 v[214:217], v[62:65], v[66:69], v[214:217]
	v_exp_f32_e32 v24, v24
	v_exp_f32_e32 v25, v25
	v_cvt_pk_bf16_f32 v70, v18, v19
	s_waitcnt lgkmcnt(2)
	v_mfma_f32_32x32x16_bf16 v[76:91], v[88:91], v[50:53], 0
	ds_read_b128 v[42:45], v172 offset:2048
	v_cvt_pk_bf16_f32 v71, v20, v21
	v_cvt_pk_bf16_f32 v72, v22, v23
	v_cvt_pk_bf16_f32 v73, v24, v25
	s_waitcnt lgkmcnt(2)
	s_nop 0
	v_mfma_f32_32x32x16_bf16 v[124:139], v[34:37], v[70:73], v[124:139]
	ds_read_b128 v[34:37], v75 offset:14336
	v_exp_f32_e32 v26, v26
	v_exp_f32_e32 v27, v27
	v_exp_f32_e32 v28, v28
	s_waitcnt lgkmcnt(2)
	v_mfma_f32_32x32x16_bf16 v[108:123], v[38:41], v[70:73], v[108:123]
	ds_read_b128 v[38:41], v75 offset:14848
	v_exp_f32_e32 v29, v29
	v_exp_f32_e32 v30, v30
	v_exp_f32_e32 v31, v31
	v_mfma_f32_16x16x32_bf16 v[214:217], v[62:65], v[70:73], v[214:217]
	v_exp_f32_e32 v32, v32
	v_exp_f32_e32 v33, v33
	v_cvt_pk_bf16_f32 v66, v26, v27
	s_waitcnt lgkmcnt(2)
	v_mfma_f32_32x32x16_bf16 v[92:107], v[42:45], v[54:57], v[92:107]
	ds_read_b128 v[42:45], v172 offset:2560
	v_cvt_pk_bf16_f32 v67, v28, v29
	v_cvt_pk_bf16_f32 v68, v30, v31
	v_cvt_pk_bf16_f32 v69, v32, v33
	s_waitcnt lgkmcnt(2)
	s_nop 0
	v_mfma_f32_32x32x16_bf16 v[124:139], v[34:37], v[66:69], v[124:139]
	s_waitcnt lgkmcnt(1)
	v_mfma_f32_32x32x16_bf16 v[108:123], v[38:41], v[66:69], v[108:123]
	v_mfma_f32_16x16x32_bf16 v[214:217], v[62:65], v[66:69], v[214:217]
	s_waitcnt lgkmcnt(0)
	v_mfma_f32_32x32x16_bf16 v[76:91], v[42:45], v[54:57], v[76:91]
	s_add_i32 s2, s43, 1
	s_add_u32 s44, s44, 0x1000
	s_addc_u32 s45, s45, 0
	s_add_u32 s46, s46, 0x2000
	s_addc_u32 s47, s47, 0
	s_cmp_lg_u32 s43, s26
	s_cbranch_scc0 .LBB0_552
	s_mov_b32 s43, s2
	s_add_i32 s9, s43, -1
	s_cmp_ge_u32 s9, s28
	s_mov_b64 s[2:3], -1
	s_cbranch_scc1 .LBB0_539
	s_branch .LBB0_540

.LBB0_588:
	v_mbcnt_lo_u32_b32 v218, -1, 0
	v_mbcnt_hi_u32_b32 v218, -1, v218
	v_and_b32_e32 v219, 15, v218
	v_lshlrev_b32_e32 v219, 2, v219
	ds_bpermute_b32 v220, v219, v214
	ds_bpermute_b32 v221, v219, v215
	ds_bpermute_b32 v222, v219, v216
	ds_bpermute_b32 v223, v219, v217
	v_and_b32_e32 v218, 16, v218
	v_cmp_ne_u32_e64 s[98:99], 0, v218
	s_waitcnt lgkmcnt(0)
	s_nop 1
	v_cndmask_b32_e64 v220, v220, v221, s[98:99]
	v_cndmask_b32_e64 v222, v222, v223, s[98:99]
	v_mov_b32_e32 v1, v8
	s_nop 1
	v_permlane32_swap_b32_e32 v8, v1
	v_mov_b32_e32 v0, v9
	v_add_f32_e32 v1, v8, v1
	s_nop 0
	v_permlane32_swap_b32_e32 v9, v0
	v_add_f32_e32 v1, v222, v1
	v_add_f32_e32 v0, v9, v0
	v_rcp_f32_e32 v1, v1
	v_add_f32_e32 v0, v220, v0
	v_rcp_f32_e32 v122, v0
	v_mbcnt_lo_u32_b32 v100, -1, 0
	v_mbcnt_hi_u32_b32 v100, -1, v100
	v_mul_f32_e32 v124, s77, v1
	s_add_i32 s31, s31, s52
	v_pk_mul_f32 v[0:1], v[42:43], v[124:125] op_sel_hi:[1,0]
	s_waitcnt vmcnt(2)
	v_mov_b32_e32 v102, v116
	v_pk_fma_f32 v[42:43], v[26:27], v[122:123], v[0:1] op_sel_hi:[1,0,1] neg_lo:[0,0,1] neg_hi:[0,0,1]
	v_lshrrev_b32_e32 v0, 1, v100
	v_and_or_b32 v26, v100, 31, s31
	v_mov_b32_e32 v100, v112
	s_nop 1
	v_permlane32_swap_b32_e32 v100, v114
	v_permlane32_swap_b32_e32 v102, v118
	v_mov_b32_e32 v103, v117
	v_lshlrev_b32_e32 v116, 16, v100
	v_and_b32_e32 v117, 0xffff0000, v100
	v_lshlrev_b32_e32 v100, 16, v118
	v_pk_mul_f32 v[74:75], v[74:75], v[124:125] op_sel_hi:[1,0]
	v_mov_b32_e32 v101, v113
	v_pk_fma_f32 v[58:59], v[58:59], v[122:123], v[74:75] op_sel_hi:[1,0,1] neg_lo:[0,0,1] neg_hi:[0,0,1]
	v_mul_f32_e32 v74, 0xbfb8aa3b, v100
	v_exp_f32_e32 v74, v74
	v_permlane32_swap_b32_e32 v101, v115
	v_permlane32_swap_b32_e32 v103, v119
	v_lshlrev_b32_e32 v120, 16, v101
	v_and_b32_e32 v121, 0xffff0000, v101
	v_lshlrev_b32_e32 v106, 16, v103
	v_and_b32_e32 v101, 0xffff0000, v118
	v_pk_mul_f32 v[72:73], v[72:73], v[124:125] op_sel_hi:[1,0]
	v_mul_f32_e32 v75, 0xbfb8aa3b, v101
	v_pk_fma_f32 v[72:73], v[56:57], v[122:123], v[72:73] op_sel_hi:[1,0,1] neg_lo:[0,0,1] neg_hi:[0,0,1]
	v_add_f32_e32 v56, 1.0, v74
	v_mul_f32_e32 v74, 0xbfb8aa3b, v106
	v_exp_f32_e32 v75, v75
	v_exp_f32_e32 v74, v74
	v_lshlrev_b32_e32 v104, 16, v102
	v_and_b32_e32 v107, 0xffff0000, v103
	v_pk_mul_f32 v[70:71], v[70:71], v[124:125] op_sel_hi:[1,0]
	v_add_f32_e32 v57, 1.0, v75
	v_mul_f32_e32 v75, 0xbfb8aa3b, v107
	v_pk_fma_f32 v[70:71], v[54:55], v[122:123], v[70:71] op_sel_hi:[1,0,1] neg_lo:[0,0,1] neg_hi:[0,0,1]
	v_add_f32_e32 v54, 1.0, v74
	v_mul_f32_e32 v74, 0xbfb8aa3b, v104
	v_exp_f32_e32 v75, v75
	v_exp_f32_e32 v74, v74
	v_lshlrev_b32_e32 v112, 16, v114
	v_and_b32_e32 v113, 0xffff0000, v114
	v_lshlrev_b32_e32 v114, 16, v115
	v_and_b32_e32 v105, 0xffff0000, v102
	v_pk_mul_f32 v[68:69], v[68:69], v[124:125] op_sel_hi:[1,0]
	v_add_f32_e32 v55, 1.0, v75
	v_mul_f32_e32 v75, 0xbfb8aa3b, v105
	v_pk_fma_f32 v[68:69], v[52:53], v[122:123], v[68:69] op_sel_hi:[1,0,1] neg_lo:[0,0,1] neg_hi:[0,0,1]
	v_add_f32_e32 v52, 1.0, v74
	v_mul_f32_e32 v74, 0xbfb8aa3b, v114
	v_exp_f32_e32 v75, v75
	v_exp_f32_e32 v74, v74
	v_and_b32_e32 v115, 0xffff0000, v115
	v_pk_mul_f32 v[66:67], v[66:67], v[124:125] op_sel_hi:[1,0]
	v_add_f32_e32 v53, 1.0, v75
	v_mul_f32_e32 v75, 0xbfb8aa3b, v115
	v_pk_fma_f32 v[66:67], v[50:51], v[122:123], v[66:67] op_sel_hi:[1,0,1] neg_lo:[0,0,1] neg_hi:[0,0,1]
	v_add_f32_e32 v50, 1.0, v74
	v_mul_f32_e32 v74, 0xbfb8aa3b, v112
	v_exp_f32_e32 v75, v75
	v_exp_f32_e32 v74, v74
	v_pk_mul_f32 v[64:65], v[64:65], v[124:125] op_sel_hi:[1,0]
	v_pk_mul_f32 v[60:61], v[60:61], v[124:125] op_sel_hi:[1,0]
	v_add_f32_e32 v51, 1.0, v75
	v_mul_f32_e32 v75, 0xbfb8aa3b, v113
	v_pk_fma_f32 v[64:65], v[48:49], v[122:123], v[64:65] op_sel_hi:[1,0,1] neg_lo:[0,0,1] neg_hi:[0,0,1]
	v_add_f32_e32 v48, 1.0, v74
	v_mul_f32_e32 v74, 0xbfb8aa3b, v120
	v_exp_f32_e32 v75, v75
	v_exp_f32_e32 v74, v74
	s_mov_b32 s0, s97
	v_and_b32_e32 v172, 16, v0
	v_lshlrev_b32_e32 v102, 16, v119
	v_and_b32_e32 v103, 0xffff0000, v119
	v_pk_fma_f32 v[118:119], v[44:45], v[122:123], v[60:61] op_sel_hi:[1,0,1] neg_lo:[0,0,1] neg_hi:[0,0,1]
	v_mul_f32_e32 v45, 0xbfb8aa3b, v116
	global_load_dwordx4 v[96:99], v172, s[60:61]
	global_load_dwordx4 v[92:95], v172, s[60:61] offset:32
	global_load_dwordx4 v[88:91], v172, s[60:61] offset:64
	global_load_dwordx4 v[84:87], v172, s[60:61] offset:96
	global_load_dwordx4 v[80:83], v172, s[60:61] offset:128
	global_load_dwordx4 v[76:79], v172, s[60:61] offset:160
	global_load_dwordx4 v[8:11], v172, s[60:61] offset:192
	global_load_dwordx4 v[0:3], v172, s[60:61] offset:224
	v_pk_mul_f32 v[62:63], v[62:63], v[124:125] op_sel_hi:[1,0]
	v_exp_f32_e32 v45, v45
	v_mul_f32_e32 v60, 0xbfb8aa3b, v117
	v_add_f32_e32 v49, 1.0, v75
	v_mul_f32_e32 v75, 0xbfb8aa3b, v121
	v_pk_fma_f32 v[62:63], v[46:47], v[122:123], v[62:63] op_sel_hi:[1,0,1] neg_lo:[0,0,1] neg_hi:[0,0,1]
	v_add_f32_e32 v46, 1.0, v74
	v_exp_f32_e32 v74, v60
	v_exp_f32_e32 v75, v75
	v_mul_f32_e32 v44, v119, v119
	v_pk_fma_f32 v[60:61], v[118:119], v[118:119], v[44:45] op_sel_hi:[1,1,0]
	v_add_f32_e32 v44, 1.0, v45
	v_add_f32_e32 v45, 1.0, v74
	v_pk_fma_f32 v[60:61], v[62:63], v[62:63], v[60:61]
	v_mul_f32_e32 v74, v63, v63
	v_pk_add_f32 v[60:61], v[74:75], v[60:61] op_sel_hi:[0,1]
	v_pk_fma_f32 v[60:61], v[64:65], v[64:65], v[60:61]
	v_mul_f32_e32 v74, v65, v65
	v_pk_add_f32 v[60:61], v[74:75], v[60:61] op_sel_hi:[0,1]
	v_pk_fma_f32 v[60:61], v[66:67], v[66:67], v[60:61]
	v_mul_f32_e32 v74, v67, v67
	v_pk_add_f32 v[60:61], v[74:75], v[60:61] op_sel_hi:[0,1]
	v_pk_fma_f32 v[60:61], v[68:69], v[68:69], v[60:61]
	v_mul_f32_e32 v74, v69, v69
	v_pk_add_f32 v[60:61], v[74:75], v[60:61] op_sel_hi:[0,1]
	v_pk_fma_f32 v[60:61], v[70:71], v[70:71], v[60:61]
	v_mul_f32_e32 v74, v71, v71
	v_pk_add_f32 v[60:61], v[74:75], v[60:61] op_sel_hi:[0,1]
	v_pk_fma_f32 v[60:61], v[72:73], v[72:73], v[60:61]
	v_mul_f32_e32 v74, v73, v73
	v_add_f32_e32 v47, 1.0, v75
	v_pk_add_f32 v[60:61], v[74:75], v[60:61] op_sel_hi:[0,1]
	v_mul_f32_e32 v75, 0xbfb8aa3b, v102
	v_exp_f32_e32 v75, v75
	v_mul_f32_e32 v123, 0xbfb8aa3b, v103
	v_exp_f32_e32 v123, v123
	v_pk_fma_f32 v[60:61], v[58:59], v[58:59], v[60:61]
	v_mul_f32_e32 v74, v59, v59
	v_pk_add_f32 v[134:135], v[74:75], v[60:61] op_sel_hi:[0,1]
	v_add_f32_e32 v60, 1.0, v75
	v_rcp_f32_e32 v132, v60
	v_add_f32_e32 v60, 1.0, v123
	v_rcp_f32_e32 v133, v60
	s_waitcnt vmcnt(8)
	v_mov_b32_e32 v60, v108
	v_mov_b32_e32 v61, v109
	s_nop 0
	v_permlane32_swap_b32_e32 v60, v110
	v_permlane32_swap_b32_e32 v61, v111
	v_lshlrev_b32_e32 v74, 16, v60
	v_and_b32_e32 v75, 0xffff0000, v60
	v_lshlrev_b32_e32 v60, 16, v61
	v_and_b32_e32 v61, 0xffff0000, v61
	v_pk_mul_f32 v[40:41], v[40:41], v[124:125] op_sel_hi:[1,0]
	v_pk_mul_f32 v[38:39], v[38:39], v[124:125] op_sel_hi:[1,0]
	v_pk_fma_f32 v[24:25], v[24:25], v[122:123], v[40:41] op_sel_hi:[1,0,1] neg_lo:[0,0,1] neg_hi:[0,0,1]
	v_mul_f32_e32 v41, 0xbfb8aa3b, v61
	v_exp_f32_e32 v41, v41
	v_mul_f32_e32 v40, 0xbfb8aa3b, v60
	v_exp_f32_e32 v40, v40
	v_pk_fma_f32 v[22:23], v[22:23], v[122:123], v[38:39] op_sel_hi:[1,0,1] neg_lo:[0,0,1] neg_hi:[0,0,1]
	v_add_f32_e32 v39, 1.0, v41
	v_mul_f32_e32 v41, 0xbfb8aa3b, v75
	v_exp_f32_e32 v41, v41
	v_permlane32_swap_b32_e32 v5, v7
	v_add_f32_e32 v38, 1.0, v40
	v_mul_f32_e32 v40, 0xbfb8aa3b, v74
	v_and_b32_e32 v109, 0xffff0000, v7
	v_pk_mul_f32 v[36:37], v[36:37], v[124:125] op_sel_hi:[1,0]
	v_exp_f32_e32 v40, v40
	v_pk_fma_f32 v[20:21], v[20:21], v[122:123], v[36:37] op_sel_hi:[1,0,1] neg_lo:[0,0,1] neg_hi:[0,0,1]
	v_add_f32_e32 v37, 1.0, v41
	v_mul_f32_e32 v41, 0xbfb8aa3b, v109
	v_exp_f32_e32 v41, v41
	v_lshlrev_b32_e32 v108, 16, v7
	v_permlane32_swap_b32_e32 v4, v6
	v_add_f32_e32 v36, 1.0, v40
	v_mul_f32_e32 v40, 0xbfb8aa3b, v108
	v_and_b32_e32 v127, 0xffff0000, v6
	v_pk_mul_f32 v[34:35], v[34:35], v[124:125] op_sel_hi:[1,0]
	v_exp_f32_e32 v40, v40
	v_pk_fma_f32 v[18:19], v[18:19], v[122:123], v[34:35] op_sel_hi:[1,0,1] neg_lo:[0,0,1] neg_hi:[0,0,1]
	v_add_f32_e32 v35, 1.0, v41
	v_mul_f32_e32 v41, 0xbfb8aa3b, v127
	v_exp_f32_e32 v41, v41
	v_lshlrev_b32_e32 v126, 16, v6
	v_add_f32_e32 v34, 1.0, v40
	v_mul_f32_e32 v40, 0xbfb8aa3b, v126
	v_and_b32_e32 v129, 0xffff0000, v5
	v_pk_mul_f32 v[32:33], v[32:33], v[124:125] op_sel_hi:[1,0]
	v_exp_f32_e32 v40, v40
	v_pk_fma_f32 v[16:17], v[16:17], v[122:123], v[32:33] op_sel_hi:[1,0,1] neg_lo:[0,0,1] neg_hi:[0,0,1]
	v_add_f32_e32 v33, 1.0, v41
	v_mul_f32_e32 v41, 0xbfb8aa3b, v129
	v_exp_f32_e32 v41, v41
	v_lshlrev_b32_e32 v128, 16, v5
	v_lshlrev_b32_e32 v130, 16, v4
	v_add_f32_e32 v32, 1.0, v40
	v_mul_f32_e32 v40, 0xbfb8aa3b, v128
	v_pk_mul_f32 v[28:29], v[28:29], v[124:125] op_sel_hi:[1,0]
	v_pk_mul_f32 v[30:31], v[30:31], v[124:125] op_sel_hi:[1,0]
	v_exp_f32_e32 v40, v40
	v_pk_fma_f32 v[12:13], v[12:13], v[122:123], v[28:29] op_sel_hi:[1,0,1] neg_lo:[0,0,1] neg_hi:[0,0,1]
	v_mul_f32_e32 v28, 0xbfb8aa3b, v130
	v_pk_fma_f32 v[14:15], v[14:15], v[122:123], v[30:31] op_sel_hi:[1,0,1] neg_lo:[0,0,1] neg_hi:[0,0,1]
	v_add_f32_e32 v31, 1.0, v41
	v_exp_f32_e32 v41, v28
	v_and_b32_e32 v131, 0xffff0000, v4
	v_add_f32_e32 v30, 1.0, v40
	v_pk_fma_f32 v[28:29], v[12:13], v[12:13], v[134:135]
	v_mul_f32_e32 v40, v13, v13
	v_pk_add_f32 v[28:29], v[40:41], v[28:29] op_sel_hi:[0,1]
	v_mul_f32_e32 v40, 0xbfb8aa3b, v131
	v_lshlrev_b32_e32 v6, 16, v110
	v_and_b32_e32 v7, 0xffff0000, v110
	v_add_f32_e32 v41, 1.0, v41
	v_exp_f32_e32 v110, v40
	v_pk_fma_f32 v[28:29], v[14:15], v[14:15], v[28:29]
	v_mul_f32_e32 v40, v15, v15
	v_pk_add_f32 v[28:29], v[40:41], v[28:29] op_sel_hi:[0,1]
	v_pk_fma_f32 v[28:29], v[16:17], v[16:17], v[28:29]
	v_mul_f32_e32 v40, v17, v17
	v_pk_add_f32 v[28:29], v[40:41], v[28:29] op_sel_hi:[0,1]
	v_pk_fma_f32 v[28:29], v[18:19], v[18:19], v[28:29]
	v_mul_f32_e32 v40, v19, v19
	v_pk_add_f32 v[28:29], v[40:41], v[28:29] op_sel_hi:[0,1]
	v_pk_fma_f32 v[28:29], v[20:21], v[20:21], v[28:29]
	v_mul_f32_e32 v40, v21, v21
	v_pk_add_f32 v[28:29], v[40:41], v[28:29] op_sel_hi:[0,1]
	v_pk_fma_f32 v[28:29], v[22:23], v[22:23], v[28:29]
	v_mul_f32_e32 v40, v23, v23
	v_pk_add_f32 v[28:29], v[40:41], v[28:29] op_sel_hi:[0,1]
	v_pk_fma_f32 v[28:29], v[24:25], v[24:25], v[28:29]
	v_mul_f32_e32 v40, v25, v25
	v_pk_add_f32 v[28:29], v[40:41], v[28:29] op_sel_hi:[0,1]
	v_pk_fma_f32 v[28:29], v[42:43], v[42:43], v[28:29]
	v_mul_f32_e32 v40, v43, v43
	v_pk_add_f32 v[28:29], v[40:41], v[28:29] op_sel_hi:[0,1]
	v_mov_b32_e32 v29, v28
	s_nop 1
	v_permlane32_swap_b32_e32 v28, v29
	v_add_f32_e32 v28, v28, v29
	v_fmamk_f32 v28, v28, 0x3c800000, v204
	v_rsq_f32_e32 v40, v28
	v_rcp_f32_e32 v44, v44
	v_rcp_f32_e32 v45, v45
	v_rcp_f32_e32 v46, v46
	v_mul_f32_e32 v40, s78, v40
	v_rcp_f32_e32 v47, v47
	s_waitcnt vmcnt(7)
	v_pk_mul_f32 v[96:97], v[96:97], v[40:41] op_sel_hi:[1,0]
	v_rcp_f32_e32 v48, v48
	v_rcp_f32_e32 v49, v49
	v_pk_mul_f32 v[96:97], v[118:119], v[96:97]
	v_pk_mul_f32 v[98:99], v[98:99], v[40:41] op_sel_hi:[1,0]
	s_waitcnt vmcnt(1)
	v_pk_mul_f32 v[8:9], v[40:41], v[8:9] op_sel_hi:[0,1]
	s_waitcnt vmcnt(0)
	v_pk_mul_f32 v[0:1], v[40:41], v[0:1] op_sel_hi:[0,1]
	v_rcp_f32_e32 v50, v50
	v_rcp_f32_e32 v51, v51
	v_pk_mul_f32 v[62:63], v[62:63], v[98:99]
	v_pk_mul_f32 v[92:93], v[92:93], v[40:41] op_sel_hi:[1,0]
	v_pk_mul_f32 v[80:81], v[80:81], v[40:41] op_sel_hi:[1,0]
	v_pk_mul_f32 v[20:21], v[20:21], v[8:9]
	v_pk_mul_f32 v[8:9], v[40:41], v[10:11] op_sel_hi:[0,1]
	v_pk_mul_f32 v[24:25], v[24:25], v[0:1]
	v_pk_mul_f32 v[0:1], v[96:97], v[116:117]
	v_rcp_f32_e32 v52, v52
	v_rcp_f32_e32 v53, v53
	v_pk_mul_f32 v[64:65], v[64:65], v[92:93]
	v_pk_mul_f32 v[92:93], v[94:95], v[40:41] op_sel_hi:[1,0]
	v_pk_mul_f32 v[80:81], v[12:13], v[80:81]
	v_pk_mul_f32 v[12:13], v[82:83], v[40:41] op_sel_hi:[1,0]
	v_pk_mul_f32 v[22:23], v[22:23], v[8:9]
	v_pk_mul_f32 v[0:1], v[0:1], v[44:45]
	v_pk_mul_f32 v[8:9], v[62:63], v[120:121]
	v_rcp_f32_e32 v54, v54
	v_rcp_f32_e32 v55, v55
	v_pk_mul_f32 v[66:67], v[66:67], v[92:93]
	v_pk_mul_f32 v[88:89], v[88:89], v[40:41] op_sel_hi:[1,0]
	v_pk_mul_f32 v[82:83], v[14:15], v[12:13]
	v_pk_mul_f32 v[12:13], v[40:41], v[76:77] op_sel_hi:[0,1]
	v_pk_mul_f32 v[10:11], v[8:9], v[46:47]
	v_cvt_pk_bf16_f32 v8, v0, v1
	v_pk_mul_f32 v[0:1], v[64:65], v[112:113]
	v_rcp_f32_e32 v56, v56
	v_rcp_f32_e32 v57, v57
	v_pk_mul_f32 v[68:69], v[68:69], v[88:89]
	v_pk_mul_f32 v[88:89], v[90:91], v[40:41] op_sel_hi:[1,0]
	v_pk_mul_f32 v[16:17], v[16:17], v[12:13]
	v_pk_mul_f32 v[12:13], v[40:41], v[78:79] op_sel_hi:[0,1]
	v_cvt_pk_bf16_f32 v9, v10, v11
	v_pk_mul_f32 v[0:1], v[0:1], v[48:49]
	v_pk_mul_f32 v[10:11], v[66:67], v[114:115]
	v_ashrrev_i32_e32 v27, 31, v26
	v_add_f32_e32 v29, 1.0, v110
	v_pk_mul_f32 v[70:71], v[70:71], v[88:89]
	v_pk_mul_f32 v[84:85], v[84:85], v[40:41] op_sel_hi:[1,0]
	v_pk_mul_f32 v[18:19], v[18:19], v[12:13]
	v_pk_mul_f32 v[12:13], v[10:11], v[50:51]
	v_cvt_pk_bf16_f32 v10, v0, v1
	v_pk_mul_f32 v[0:1], v[68:69], v[104:105]
	v_lshlrev_b64 v[26:27], 11, v[26:27]
	v_rcp_f32_e32 v28, v41
	v_rcp_f32_e32 v29, v29
	v_pk_mul_f32 v[72:73], v[72:73], v[84:85]
	v_pk_mul_f32 v[84:85], v[86:87], v[40:41] op_sel_hi:[1,0]
	v_cvt_pk_bf16_f32 v11, v12, v13
	v_pk_mul_f32 v[0:1], v[0:1], v[52:53]
	v_pk_mul_f32 v[12:13], v[70:71], v[106:107]
	v_lshl_add_u64 v[26:27], s[58:59], 0, v[26:27]
	s_lshl_b32 s0, s51, 1
	s_mov_b32 s1, s8
	v_rcp_f32_e32 v30, v30
	v_rcp_f32_e32 v31, v31
	v_pk_mul_f32 v[58:59], v[58:59], v[84:85]
	v_pk_mul_f32 v[14:15], v[12:13], v[54:55]
	v_cvt_pk_bf16_f32 v12, v0, v1
	v_pk_mul_f32 v[0:1], v[72:73], v[100:101]
	v_lshl_add_u64 v[26:27], v[26:27], 0, s[0:1]
	v_rcp_f32_e32 v32, v32
	v_rcp_f32_e32 v33, v33
	v_cvt_pk_bf16_f32 v13, v14, v15
	v_pk_mul_f32 v[0:1], v[0:1], v[56:57]
	v_pk_mul_f32 v[14:15], v[58:59], v[102:103]
	v_lshl_add_u64 v[26:27], v[26:27], 0, v[172:173]
	v_rcp_f32_e32 v34, v34
	v_rcp_f32_e32 v35, v35
	v_pk_mul_f32 v[44:45], v[14:15], v[132:133]
	v_cvt_pk_bf16_f32 v14, v0, v1
	v_permlane32_swap_b32_e32 v8, v10
	v_permlane32_swap_b32_e32 v9, v11
	v_pk_mul_f32 v[0:1], v[80:81], v[130:131]
	v_rcp_f32_e32 v36, v36
	v_rcp_f32_e32 v37, v37
	global_store_dwordx4 v[26:27], v[8:11], off offset:1024
	v_pk_mul_f32 v[0:1], v[0:1], v[28:29]
	v_rcp_f32_e32 v38, v38
	v_pk_mul_f32 v[8:9], v[82:83], v[128:129]
	v_rcp_f32_e32 v39, v39
	v_cvt_pk_bf16_f32 v15, v44, v45
	v_pk_mul_f32 v[10:11], v[8:9], v[30:31]
	v_cvt_pk_bf16_f32 v8, v0, v1
	v_pk_mul_f32 v[0:1], v[16:17], v[126:127]
	v_permlane32_swap_b32_e32 v12, v14
	v_permlane32_swap_b32_e32 v13, v15
	v_cvt_pk_bf16_f32 v9, v10, v11
	v_pk_mul_f32 v[0:1], v[0:1], v[32:33]
	v_pk_mul_f32 v[10:11], v[18:19], v[108:109]
	global_store_dwordx4 v[26:27], v[12:15], off offset:1056
	v_lshlrev_b32_e32 v4, 16, v111
	v_and_b32_e32 v5, 0xffff0000, v111
	v_pk_mul_f32 v[12:13], v[10:11], v[34:35]
	v_cvt_pk_bf16_f32 v10, v0, v1
	v_pk_mul_f32 v[0:1], v[20:21], v[74:75]
	v_cvt_pk_bf16_f32 v11, v12, v13
	v_pk_mul_f32 v[0:1], v[0:1], v[36:37]
	v_pk_mul_f32 v[12:13], v[22:23], v[60:61]
	v_cvt_pk_bf16_f32 v0, v0, v1
	v_pk_mul_f32 v[12:13], v[12:13], v[38:39]
	v_mul_f32_e32 v1, 0xbfb8aa3b, v6
	v_exp_f32_e32 v14, v1
	v_cvt_pk_bf16_f32 v1, v12, v13
	v_mul_f32_e32 v12, 0xbfb8aa3b, v7
	v_exp_f32_e32 v13, v12
	v_add_f32_e32 v12, 1.0, v14
	v_mul_f32_e32 v14, 0xbfb8aa3b, v4
	v_mul_f32_e32 v15, 0xbfb8aa3b, v5
	v_add_f32_e32 v13, 1.0, v13
	v_rcp_f32_e32 v12, v12
	v_rcp_f32_e32 v13, v13
	v_exp_f32_e32 v14, v14
	v_exp_f32_e32 v15, v15
	v_pk_mul_f32 v[6:7], v[24:25], v[6:7]
	v_pk_mul_f32 v[2:3], v[40:41], v[2:3] op_sel_hi:[0,1]
	v_pk_mul_f32 v[6:7], v[6:7], v[12:13]
	v_add_f32_e32 v12, 1.0, v14
	v_add_f32_e32 v13, 1.0, v15
	v_rcp_f32_e32 v12, v12
	v_rcp_f32_e32 v13, v13
	v_pk_mul_f32 v[2:3], v[42:43], v[2:3]
	v_permlane32_swap_b32_e32 v8, v10
	v_pk_mul_f32 v[2:3], v[2:3], v[4:5]
	v_permlane32_swap_b32_e32 v9, v11
	v_pk_mul_f32 v[4:5], v[2:3], v[12:13]
	v_cvt_pk_bf16_f32 v2, v6, v7
	v_cvt_pk_bf16_f32 v3, v4, v5
	s_nop 0
	v_permlane32_swap_b32_e32 v0, v2
	v_permlane32_swap_b32_e32 v1, v3
	global_store_dwordx4 v[26:27], v[8:11], off offset:1088
	global_store_dwordx4 v[26:27], v[0:3], off offset:1120
	s_setprio 0
	s_waitcnt lgkmcnt(0)
	s_barrier

	.amdhsa_kernel _ZN2fx10fwd_kernelENS_6ParamsE
		.amdhsa_group_segment_fixed_size 0
		.amdhsa_private_segment_fixed_size 0
		.amdhsa_kernarg_size 440
		.amdhsa_user_sgpr_count 2
		.amdhsa_user_sgpr_dispatch_ptr 0
		.amdhsa_user_sgpr_queue_ptr 0
		.amdhsa_user_sgpr_kernarg_segment_ptr 1
		.amdhsa_user_sgpr_dispatch_id 0
		.amdhsa_user_sgpr_kernarg_preload_length 0
		.amdhsa_user_sgpr_kernarg_preload_offset 0
		.amdhsa_user_sgpr_private_segment_size 0
		.amdhsa_uses_dynamic_stack 0
		.amdhsa_enable_private_segment 0
		.amdhsa_system_sgpr_workgroup_id_x 1
		.amdhsa_system_sgpr_workgroup_id_y 0
		.amdhsa_system_sgpr_workgroup_id_z 0
		.amdhsa_system_sgpr_workgroup_info 0
		.amdhsa_system_vgpr_workitem_id 2
		.amdhsa_next_free_vgpr 244
		.amdhsa_next_free_sgpr 100
		.amdhsa_accum_offset 244
		.amdhsa_reserve_vcc 1
		.amdhsa_float_round_mode_32 0
		.amdhsa_float_round_mode_16_64 0
		.amdhsa_float_denorm_mode_32 3
		.amdhsa_float_denorm_mode_16_64 3
		.amdhsa_dx10_clamp 1
		.amdhsa_ieee_mode 1
		.amdhsa_fp16_overflow 0
		.amdhsa_tg_split 0
		.amdhsa_exception_fp_ieee_invalid_op 0
		.amdhsa_exception_fp_denorm_src 0
		.amdhsa_exception_fp_ieee_div_zero 0
		.amdhsa_exception_fp_ieee_overflow 0
		.amdhsa_exception_fp_ieee_underflow 0
		.amdhsa_exception_fp_ieee_inexact 0
		.amdhsa_exception_int_div_zero 0
	.end_amdhsa_kernel

amdhsa.kernels:
  - .agpr_count:     0
    .args:
      - .offset:         0
        .size:           184
        .value_kind:     by_value
      - .offset:         184
        .size:           4
        .value_kind:     hidden_block_count_x
      - .offset:         188
        .size:           4
        .value_kind:     hidden_block_count_y
      - .offset:         192
        .size:           4
        .value_kind:     hidden_block_count_z
      - .offset:         196
        .size:           2
        .value_kind:     hidden_group_size_x
      - .offset:         198
        .size:           2
        .value_kind:     hidden_group_size_y
      - .offset:         200
        .size:           2
        .value_kind:     hidden_group_size_z
      - .offset:         202
        .size:           2
        .value_kind:     hidden_remainder_x
      - .offset:         204
        .size:           2
        .value_kind:     hidden_remainder_y
      - .offset:         206
        .size:           2
        .value_kind:     hidden_remainder_z
      - .offset:         224
        .size:           8
        .value_kind:     hidden_global_offset_x
      - .offset:         232
        .size:           8
        .value_kind:     hidden_global_offset_y
      - .offset:         240
        .size:           8
        .value_kind:     hidden_global_offset_z
      - .offset:         248
        .size:           2
        .value_kind:     hidden_grid_dims
      - .offset:         272
        .size:           8
        .value_kind:     hidden_multigrid_sync_arg
      - .offset:         304
        .size:           4
        .value_kind:     hidden_dynamic_lds_size
    .group_segment_fixed_size: 0
    .kernarg_segment_align: 8
    .kernarg_segment_size: 440
    .language:       OpenCL C
    .language_version:
      - 2
      - 0
    .max_flat_workgroup_size: 512
    .name:           _ZN2fx10fwd_kernelENS_6ParamsE
    .private_segment_fixed_size: 0
    .sgpr_count:     106
    .sgpr_spill_count: 77
    .symbol:         _ZN2fx10fwd_kernelENS_6ParamsE.kd
    .uniform_work_group_size: 1
    .uses_dynamic_stack: false
    .vgpr_count:     244
    .vgpr_spill_count: 0
    .wavefront_size: 64
